# P7 output stores without the nt hint
# speedup vs baseline: 1.0001x; 1.0001x over previous
; __device__ __forceinline__ f32x4 unpack4(const u32x2& w) { f32x4 a; a[0] = __uint_as_float(w.x << 16); a[1] = __uint_as_float(w.x & 0xffff0000u); a[2] = __uint_as_float(w.y << 16); a[3] = __uint_as_float(w.y & 0xffff0000u); return a; }
; __global__ void __launch_bounds__(512, 2) hymba_fwd(Params p) {
;     ...
;         for (int m0 = 2 * gw; m0 < MT; m0 += 2 * NGW) { const int m1 = m0 + 1;
;             const float r0 = rsqrtf(ss3[m0] * (1.0f / DM) + EPS), r1 = rsqrtf(ss3[m1] * (1.0f / DM) + EPS);
;             u32x2 h0[4], h1[4];
; #pragma unroll
;             for (int j = 0; j < 4; ++j) { h0[j] = __builtin_nontemporal_load((const u32x2*)(H3 + (size_t)m0 * DM) + lane + 64 * j); h1[j] = __builtin_nontemporal_load((const u32x2*)(H3 + (size_t)m1 * DM) + lane + 64 * j); }
; #pragma unroll
;             for (int j = 0; j < 4; ++j) { __builtin_nontemporal_store(unpack4(h0[j]) * r0 * gv[j], (f32x4*)(p.out + (size_t)m0 * DM) + lane + 64 * j); __builtin_nontemporal_store(unpack4(h1[j]) * r1 * gv[j], (f32x4*)(p.out + (size_t)m1 * DM) + lane + 64 * j); } }
.Lp7s_skip1:
.LBB0_955:
	v_lshl_add_u64 v[26:27], s[64:65], 0, v[18:19]
	global_load_dwordx2 v[26:27], v[26:27], off
	v_lshl_add_u64 v[28:29], s[64:65], 0, v[20:21]
	v_add_co_u32_e32 v30, vcc, s13, v28
	v_add_u32_e32 v16, s2, v16
	s_nop 0
	v_addc_co_u32_e32 v31, vcc, 0, v29, vcc
	v_add_co_u32_e32 v28, vcc, s14, v28
	v_lshl_add_u64 v[18:19], v[18:19], 0, s[4:5]
	s_nop 0
	v_addc_co_u32_e32 v29, vcc, 0, v29, vcc
	global_load_dwordx2 v[32:33], v[30:31], off offset:3584 nt
	global_load_dwordx2 v[34:35], v[28:29], off offset:1536 nt
	global_load_dwordx2 v[36:37], v[28:29], off nt
	global_load_dwordx2 v[38:39], v[28:29], off offset:2048 nt
	global_load_dwordx2 v[40:41], v[28:29], off offset:512 nt
	global_load_dwordx2 v[42:43], v[28:29], off offset:2560 nt
	global_load_dwordx2 v[44:45], v[28:29], off offset:1024 nt
	global_load_dwordx2 v[46:47], v[28:29], off offset:3072 nt
	v_cmp_lt_i32_e32 vcc, s15, v16
	s_or_b64 s[10:11], vcc, s[10:11]
	v_lshl_add_u64 v[20:21], v[20:21], 0, s[6:7]
	s_mov_b64 s[98:99], exec
	s_andn2_b64 exec, exec, s[10:11]
	s_cbranch_execz .Lp7_single
	v_lshl_add_u64 v[70:71], s[64:65], 0, v[18:19]
	global_load_dwordx2 v[70:71], v[70:71], off
	v_lshl_add_u64 v[88:89], s[64:65], 0, v[20:21]
	v_add_co_u32_e32 v90, vcc, s13, v88
	v_add_u32_e32 v16, s2, v16
	s_nop 0
	v_addc_co_u32_e32 v91, vcc, 0, v89, vcc
	v_add_co_u32_e32 v88, vcc, s14, v88
	v_lshl_add_u64 v[18:19], v[18:19], 0, s[4:5]
	s_nop 0
	v_addc_co_u32_e32 v89, vcc, 0, v89, vcc
	global_load_dwordx2 v[72:73], v[90:91], off offset:3584 nt
	global_load_dwordx2 v[74:75], v[88:89], off offset:1536 nt
	global_load_dwordx2 v[76:77], v[88:89], off nt
	global_load_dwordx2 v[78:79], v[88:89], off offset:2048 nt
	global_load_dwordx2 v[80:81], v[88:89], off offset:512 nt
	global_load_dwordx2 v[82:83], v[88:89], off offset:2560 nt
	global_load_dwordx2 v[84:85], v[88:89], off offset:1024 nt
	global_load_dwordx2 v[86:87], v[88:89], off offset:3072 nt
	v_cmp_lt_i32_e32 vcc, s15, v16
	s_or_b64 s[10:11], vcc, s[10:11]
	v_lshl_add_u64 v[20:21], v[20:21], 0, s[6:7]
	s_mov_b64 s[100:101], exec
	s_mov_b64 exec, s[98:99]
	s_waitcnt vmcnt(17)
	v_pk_fma_f32 v[26:27], v[26:27], s[12:13], v[24:25] op_sel_hi:[1,0,0]
	s_nop 0
	v_mul_f32_e32 v17, 0x4b800000, v26
	v_cmp_gt_f32_e64 s[0:1], s3, v26
	v_mul_f32_e32 v25, 0x4b800000, v27
	v_cmp_gt_f32_e32 vcc, s3, v27
	v_cndmask_b32_e64 v17, v26, v17, s[0:1]
	v_rsq_f32_e32 v17, v17
	v_cndmask_b32_e32 v25, v27, v25, vcc
	v_rsq_f32_e32 v25, v25
	s_waitcnt vmcnt(16)
	v_lshlrev_b32_e32 v28, 16, v32
	v_mul_f32_e32 v26, 0x45800000, v17
	v_and_b32_e32 v29, 0xffff0000, v32
	v_lshlrev_b32_e32 v30, 16, v33
	v_and_b32_e32 v31, 0xffff0000, v33
	v_mul_f32_e32 v27, 0x45800000, v25
	v_cndmask_b32_e64 v26, v17, v26, s[0:1]
	s_waitcnt vmcnt(15)
	v_lshlrev_b32_e32 v32, 16, v34
	v_and_b32_e32 v33, 0xffff0000, v34
	v_lshlrev_b32_e32 v34, 16, v35
	v_and_b32_e32 v35, 0xffff0000, v35
	s_waitcnt vmcnt(14)
	v_lshlrev_b32_e32 v48, 16, v36
	v_and_b32_e32 v49, 0xffff0000, v36
	v_lshlrev_b32_e32 v36, 16, v37
	v_and_b32_e32 v37, 0xffff0000, v37
	s_waitcnt vmcnt(13)
	v_lshlrev_b32_e32 v50, 16, v38
	v_and_b32_e32 v51, 0xffff0000, v38
	v_lshlrev_b32_e32 v38, 16, v39
	v_and_b32_e32 v39, 0xffff0000, v39
	s_waitcnt vmcnt(12)
	v_lshlrev_b32_e32 v52, 16, v40
	v_and_b32_e32 v53, 0xffff0000, v40
	v_lshlrev_b32_e32 v40, 16, v41
	v_and_b32_e32 v41, 0xffff0000, v41
	s_waitcnt vmcnt(11)
	v_lshlrev_b32_e32 v54, 16, v42
	v_and_b32_e32 v55, 0xffff0000, v42
	v_lshlrev_b32_e32 v42, 16, v43
	v_and_b32_e32 v43, 0xffff0000, v43
	s_waitcnt vmcnt(10)
	v_lshlrev_b32_e32 v56, 16, v44
	v_and_b32_e32 v57, 0xffff0000, v44
	v_lshlrev_b32_e32 v44, 16, v45
	v_and_b32_e32 v45, 0xffff0000, v45
	s_waitcnt vmcnt(9)
	v_lshlrev_b32_e32 v58, 16, v46
	v_and_b32_e32 v59, 0xffff0000, v46
	v_lshlrev_b32_e32 v46, 16, v47
	v_and_b32_e32 v47, 0xffff0000, v47
	v_cndmask_b32_e32 v60, v25, v27, vcc
	v_pk_mul_f32 v[62:63], v[26:27], v[28:29] op_sel_hi:[0,1]
	v_pk_mul_f32 v[28:29], v[26:27], v[30:31] op_sel_hi:[0,1]
	v_pk_mul_f32 v[30:31], v[60:61], v[32:33] op_sel_hi:[0,1]
	v_pk_mul_f32 v[32:33], v[60:61], v[34:35] op_sel_hi:[0,1]
	v_pk_mul_f32 v[34:35], v[26:27], v[48:49] op_sel_hi:[0,1]
	v_pk_mul_f32 v[36:37], v[26:27], v[36:37] op_sel_hi:[0,1]
	v_pk_mul_f32 v[48:49], v[60:61], v[50:51] op_sel_hi:[0,1]
	v_pk_mul_f32 v[38:39], v[60:61], v[38:39] op_sel_hi:[0,1]
	v_pk_mul_f32 v[50:51], v[26:27], v[52:53] op_sel_hi:[0,1]
	v_pk_mul_f32 v[52:53], v[26:27], v[40:41] op_sel_hi:[0,1]
	v_pk_mul_f32 v[54:55], v[60:61], v[54:55] op_sel_hi:[0,1]
	v_pk_mul_f32 v[64:65], v[60:61], v[42:43] op_sel_hi:[0,1]
	v_pk_mul_f32 v[56:57], v[26:27], v[56:57] op_sel_hi:[0,1]
	v_pk_mul_f32 v[66:67], v[26:27], v[44:45] op_sel_hi:[0,1]
	v_pk_mul_f32 v[58:59], v[60:61], v[58:59] op_sel_hi:[0,1]
	v_pk_mul_f32 v[60:61], v[60:61], v[46:47] op_sel_hi:[0,1]
	v_pk_mul_f32 v[28:29], v[2:3], v[28:29]
	v_pk_mul_f32 v[26:27], v[0:1], v[62:63]
	v_pk_mul_f32 v[32:33], v[2:3], v[32:33]
	v_pk_mul_f32 v[30:31], v[0:1], v[30:31]
	v_pk_mul_f32 v[36:37], v[6:7], v[36:37]
	v_pk_mul_f32 v[34:35], v[4:5], v[34:35]
	v_pk_mul_f32 v[40:41], v[6:7], v[38:39]
	v_pk_mul_f32 v[38:39], v[4:5], v[48:49]
	v_pk_mul_f32 v[44:45], v[10:11], v[52:53]
	v_pk_mul_f32 v[42:43], v[8:9], v[50:51]
	v_pk_mul_f32 v[48:49], v[10:11], v[64:65]
	v_pk_mul_f32 v[46:47], v[8:9], v[54:55]
	v_pk_mul_f32 v[52:53], v[14:15], v[66:67]
	v_pk_mul_f32 v[50:51], v[12:13], v[56:57]
	v_pk_mul_f32 v[56:57], v[14:15], v[60:61]
	v_pk_mul_f32 v[54:55], v[12:13], v[58:59]
	global_store_dwordx4 v[22:23], v[26:29], off offset:-4096
	global_store_dwordx4 v[22:23], v[30:33], off
	global_store_dwordx4 v[22:23], v[34:37], off offset:-3072
	global_store_dwordx4 v[22:23], v[38:41], off offset:1024
	global_store_dwordx4 v[22:23], v[42:45], off offset:-2048
	global_store_dwordx4 v[22:23], v[46:49], off offset:2048
	global_store_dwordx4 v[22:23], v[50:53], off offset:-1024
	global_store_dwordx4 v[22:23], v[54:57], off offset:3072
	v_lshl_add_u64 v[22:23], v[22:23], 0, s[8:9]
	s_mov_b64 exec, s[100:101]
	s_waitcnt vmcnt(8)
; __device__ __forceinline__ f32x4 unpack4(const u32x2& w) { f32x4 a; a[0] = __uint_as_float(w.x << 16); a[1] = __uint_as_float(w.x & 0xffff0000u); a[2] = __uint_as_float(w.y << 16); a[3] = __uint_as_float(w.y & 0xffff0000u); return a; }
; __global__ void __launch_bounds__(512, 2) hymba_fwd(Params p) {
;     ...
;         for (int m0 = 2 * gw; m0 < MT; m0 += 2 * NGW) { const int m1 = m0 + 1;
;             const float r0 = rsqrtf(ss3[m0] * (1.0f / DM) + EPS), r1 = rsqrtf(ss3[m1] * (1.0f / DM) + EPS);
;             u32x2 h0[4], h1[4];
; #pragma unroll
;             for (int j = 0; j < 4; ++j) { h0[j] = __builtin_nontemporal_load((const u32x2*)(H3 + (size_t)m0 * DM) + lane + 64 * j); h1[j] = __builtin_nontemporal_load((const u32x2*)(H3 + (size_t)m1 * DM) + lane + 64 * j); }
; #pragma unroll
;             for (int j = 0; j < 4; ++j) { __builtin_nontemporal_store(unpack4(h0[j]) * r0 * gv[j], (f32x4*)(p.out + (size_t)m0 * DM) + lane + 64 * j); __builtin_nontemporal_store(unpack4(h1[j]) * r1 * gv[j], (f32x4*)(p.out + (size_t)m1 * DM) + lane + 64 * j); } }
	v_mov_b32_e32 v26, v70
	v_mov_b32_e32 v27, v71
	v_mov_b32_e32 v32, v72
	v_mov_b32_e32 v33, v73
	v_mov_b32_e32 v34, v74
	v_mov_b32_e32 v35, v75
	v_mov_b32_e32 v36, v76
	v_mov_b32_e32 v37, v77
	v_mov_b32_e32 v38, v78
	v_mov_b32_e32 v39, v79
	v_mov_b32_e32 v40, v80
	v_mov_b32_e32 v41, v81
	v_mov_b32_e32 v42, v82
	v_mov_b32_e32 v43, v83
	v_mov_b32_e32 v44, v84
	v_mov_b32_e32 v45, v85
	v_mov_b32_e32 v46, v86
	v_mov_b32_e32 v47, v87
	v_pk_fma_f32 v[26:27], v[26:27], s[12:13], v[24:25] op_sel_hi:[1,0,0]
	s_nop 0
	v_mul_f32_e32 v17, 0x4b800000, v26
	v_cmp_gt_f32_e64 s[0:1], s3, v26
	v_mul_f32_e32 v25, 0x4b800000, v27
	v_cmp_gt_f32_e32 vcc, s3, v27
	v_cndmask_b32_e64 v17, v26, v17, s[0:1]
	v_rsq_f32_e32 v17, v17
	v_cndmask_b32_e32 v25, v27, v25, vcc
	v_rsq_f32_e32 v25, v25
	v_lshlrev_b32_e32 v28, 16, v32
	v_mul_f32_e32 v26, 0x45800000, v17
	v_and_b32_e32 v29, 0xffff0000, v32
	v_lshlrev_b32_e32 v30, 16, v33
	v_and_b32_e32 v31, 0xffff0000, v33
	v_mul_f32_e32 v27, 0x45800000, v25
	v_cndmask_b32_e64 v26, v17, v26, s[0:1]
	v_lshlrev_b32_e32 v32, 16, v34
	v_and_b32_e32 v33, 0xffff0000, v34
	v_lshlrev_b32_e32 v34, 16, v35
	v_and_b32_e32 v35, 0xffff0000, v35
	v_lshlrev_b32_e32 v48, 16, v36
	v_and_b32_e32 v49, 0xffff0000, v36
	v_lshlrev_b32_e32 v36, 16, v37
	v_and_b32_e32 v37, 0xffff0000, v37
	v_lshlrev_b32_e32 v50, 16, v38
	v_and_b32_e32 v51, 0xffff0000, v38
	v_lshlrev_b32_e32 v38, 16, v39
	v_and_b32_e32 v39, 0xffff0000, v39
	v_lshlrev_b32_e32 v52, 16, v40
	v_and_b32_e32 v53, 0xffff0000, v40
	v_lshlrev_b32_e32 v40, 16, v41
	v_and_b32_e32 v41, 0xffff0000, v41
	v_lshlrev_b32_e32 v54, 16, v42
	v_and_b32_e32 v55, 0xffff0000, v42
	v_lshlrev_b32_e32 v42, 16, v43
	v_and_b32_e32 v43, 0xffff0000, v43
	v_lshlrev_b32_e32 v56, 16, v44
	v_and_b32_e32 v57, 0xffff0000, v44
	v_lshlrev_b32_e32 v44, 16, v45
	v_and_b32_e32 v45, 0xffff0000, v45
	v_lshlrev_b32_e32 v58, 16, v46
	v_and_b32_e32 v59, 0xffff0000, v46
	v_lshlrev_b32_e32 v46, 16, v47
	v_and_b32_e32 v47, 0xffff0000, v47
	v_cndmask_b32_e32 v60, v25, v27, vcc
	v_pk_mul_f32 v[62:63], v[26:27], v[28:29] op_sel_hi:[0,1]
	v_pk_mul_f32 v[28:29], v[26:27], v[30:31] op_sel_hi:[0,1]
	v_pk_mul_f32 v[30:31], v[60:61], v[32:33] op_sel_hi:[0,1]
	v_pk_mul_f32 v[32:33], v[60:61], v[34:35] op_sel_hi:[0,1]
	v_pk_mul_f32 v[34:35], v[26:27], v[48:49] op_sel_hi:[0,1]
	v_pk_mul_f32 v[36:37], v[26:27], v[36:37] op_sel_hi:[0,1]
	v_pk_mul_f32 v[48:49], v[60:61], v[50:51] op_sel_hi:[0,1]
	v_pk_mul_f32 v[38:39], v[60:61], v[38:39] op_sel_hi:[0,1]
	v_pk_mul_f32 v[50:51], v[26:27], v[52:53] op_sel_hi:[0,1]
	v_pk_mul_f32 v[52:53], v[26:27], v[40:41] op_sel_hi:[0,1]
	v_pk_mul_f32 v[54:55], v[60:61], v[54:55] op_sel_hi:[0,1]
	v_pk_mul_f32 v[64:65], v[60:61], v[42:43] op_sel_hi:[0,1]
	v_pk_mul_f32 v[56:57], v[26:27], v[56:57] op_sel_hi:[0,1]
	v_pk_mul_f32 v[66:67], v[26:27], v[44:45] op_sel_hi:[0,1]
	v_pk_mul_f32 v[58:59], v[60:61], v[58:59] op_sel_hi:[0,1]
	v_pk_mul_f32 v[60:61], v[60:61], v[46:47] op_sel_hi:[0,1]
	v_pk_mul_f32 v[28:29], v[2:3], v[28:29]
	v_pk_mul_f32 v[26:27], v[0:1], v[62:63]
	v_pk_mul_f32 v[32:33], v[2:3], v[32:33]
	v_pk_mul_f32 v[30:31], v[0:1], v[30:31]
	v_pk_mul_f32 v[36:37], v[6:7], v[36:37]
	v_pk_mul_f32 v[34:35], v[4:5], v[34:35]
	v_pk_mul_f32 v[40:41], v[6:7], v[38:39]
	v_pk_mul_f32 v[38:39], v[4:5], v[48:49]
	v_pk_mul_f32 v[44:45], v[10:11], v[52:53]
	v_pk_mul_f32 v[42:43], v[8:9], v[50:51]
	v_pk_mul_f32 v[48:49], v[10:11], v[64:65]
	v_pk_mul_f32 v[46:47], v[8:9], v[54:55]
	v_pk_mul_f32 v[52:53], v[14:15], v[66:67]
	v_pk_mul_f32 v[50:51], v[12:13], v[56:57]
	v_pk_mul_f32 v[56:57], v[14:15], v[60:61]
	v_pk_mul_f32 v[54:55], v[12:13], v[58:59]
	global_store_dwordx4 v[22:23], v[26:29], off offset:-4096
	global_store_dwordx4 v[22:23], v[30:33], off
	global_store_dwordx4 v[22:23], v[34:37], off offset:-3072
	global_store_dwordx4 v[22:23], v[38:41], off offset:1024
	global_store_dwordx4 v[22:23], v[42:45], off offset:-2048
	global_store_dwordx4 v[22:23], v[46:49], off offset:2048
	global_store_dwordx4 v[22:23], v[50:53], off offset:-1024
	global_store_dwordx4 v[22:23], v[54:57], off offset:3072
	v_lshl_add_u64 v[22:23], v[22:23], 0, s[8:9]
	s_andn2_b64 exec, exec, s[10:11]
	s_cbranch_execnz .LBB0_955
	s_branch .LBB0_956
; __device__ __forceinline__ f32x4 unpack4(const u32x2& w) { f32x4 a; a[0] = __uint_as_float(w.x << 16); a[1] = __uint_as_float(w.x & 0xffff0000u); a[2] = __uint_as_float(w.y << 16); a[3] = __uint_as_float(w.y & 0xffff0000u); return a; }
; __global__ void __launch_bounds__(512, 2) hymba_fwd(Params p) {
;     ...
;         for (int m0 = 2 * gw; m0 < MT; m0 += 2 * NGW) { const int m1 = m0 + 1;
;             const float r0 = rsqrtf(ss3[m0] * (1.0f / DM) + EPS), r1 = rsqrtf(ss3[m1] * (1.0f / DM) + EPS);
;             u32x2 h0[4], h1[4];
; #pragma unroll
;             for (int j = 0; j < 4; ++j) { h0[j] = __builtin_nontemporal_load((const u32x2*)(H3 + (size_t)m0 * DM) + lane + 64 * j); h1[j] = __builtin_nontemporal_load((const u32x2*)(H3 + (size_t)m1 * DM) + lane + 64 * j); }
; #pragma unroll
;             for (int j = 0; j < 4; ++j) { __builtin_nontemporal_store(unpack4(h0[j]) * r0 * gv[j], (f32x4*)(p.out + (size_t)m0 * DM) + lane + 64 * j); __builtin_nontemporal_store(unpack4(h1[j]) * r1 * gv[j], (f32x4*)(p.out + (size_t)m1 * DM) + lane + 64 * j); } }
.Lp7_single:
	s_mov_b64 exec, s[98:99]
	s_waitcnt vmcnt(8)
	v_pk_fma_f32 v[26:27], v[26:27], s[12:13], v[24:25] op_sel_hi:[1,0,0]
	s_nop 0
	v_mul_f32_e32 v17, 0x4b800000, v26
	v_cmp_gt_f32_e64 s[0:1], s3, v26
	v_mul_f32_e32 v25, 0x4b800000, v27
	v_cmp_gt_f32_e32 vcc, s3, v27
	v_cndmask_b32_e64 v17, v26, v17, s[0:1]
	v_rsq_f32_e32 v17, v17
	v_cndmask_b32_e32 v25, v27, v25, vcc
	v_rsq_f32_e32 v25, v25
	s_waitcnt vmcnt(7)
	v_lshlrev_b32_e32 v28, 16, v32
	v_mul_f32_e32 v26, 0x45800000, v17
	v_and_b32_e32 v29, 0xffff0000, v32
	v_lshlrev_b32_e32 v30, 16, v33
	v_and_b32_e32 v31, 0xffff0000, v33
	v_mul_f32_e32 v27, 0x45800000, v25
	v_cndmask_b32_e64 v26, v17, v26, s[0:1]
	s_waitcnt vmcnt(6)
	v_lshlrev_b32_e32 v32, 16, v34
	v_and_b32_e32 v33, 0xffff0000, v34
	v_lshlrev_b32_e32 v34, 16, v35
	v_and_b32_e32 v35, 0xffff0000, v35
	s_waitcnt vmcnt(5)
	v_lshlrev_b32_e32 v48, 16, v36
	v_and_b32_e32 v49, 0xffff0000, v36
	v_lshlrev_b32_e32 v36, 16, v37
	v_and_b32_e32 v37, 0xffff0000, v37
	s_waitcnt vmcnt(4)
	v_lshlrev_b32_e32 v50, 16, v38
	v_and_b32_e32 v51, 0xffff0000, v38
	v_lshlrev_b32_e32 v38, 16, v39
	v_and_b32_e32 v39, 0xffff0000, v39
	s_waitcnt vmcnt(3)
	v_lshlrev_b32_e32 v52, 16, v40
	v_and_b32_e32 v53, 0xffff0000, v40
	v_lshlrev_b32_e32 v40, 16, v41
	v_and_b32_e32 v41, 0xffff0000, v41
	s_waitcnt vmcnt(2)
	v_lshlrev_b32_e32 v54, 16, v42
	v_and_b32_e32 v55, 0xffff0000, v42
	v_lshlrev_b32_e32 v42, 16, v43
	v_and_b32_e32 v43, 0xffff0000, v43
	s_waitcnt vmcnt(1)
	v_lshlrev_b32_e32 v56, 16, v44
	v_and_b32_e32 v57, 0xffff0000, v44
	v_lshlrev_b32_e32 v44, 16, v45
	v_and_b32_e32 v45, 0xffff0000, v45
	s_waitcnt vmcnt(0)
	v_lshlrev_b32_e32 v58, 16, v46
	v_and_b32_e32 v59, 0xffff0000, v46
	v_lshlrev_b32_e32 v46, 16, v47
	v_and_b32_e32 v47, 0xffff0000, v47
	v_cndmask_b32_e32 v60, v25, v27, vcc
	v_pk_mul_f32 v[62:63], v[26:27], v[28:29] op_sel_hi:[0,1]
	v_pk_mul_f32 v[28:29], v[26:27], v[30:31] op_sel_hi:[0,1]
	v_pk_mul_f32 v[30:31], v[60:61], v[32:33] op_sel_hi:[0,1]
	v_pk_mul_f32 v[32:33], v[60:61], v[34:35] op_sel_hi:[0,1]
	v_pk_mul_f32 v[34:35], v[26:27], v[48:49] op_sel_hi:[0,1]
	v_pk_mul_f32 v[36:37], v[26:27], v[36:37] op_sel_hi:[0,1]
	v_pk_mul_f32 v[48:49], v[60:61], v[50:51] op_sel_hi:[0,1]
	v_pk_mul_f32 v[38:39], v[60:61], v[38:39] op_sel_hi:[0,1]
	v_pk_mul_f32 v[50:51], v[26:27], v[52:53] op_sel_hi:[0,1]
	v_pk_mul_f32 v[52:53], v[26:27], v[40:41] op_sel_hi:[0,1]
	v_pk_mul_f32 v[54:55], v[60:61], v[54:55] op_sel_hi:[0,1]
	v_pk_mul_f32 v[64:65], v[60:61], v[42:43] op_sel_hi:[0,1]
	v_pk_mul_f32 v[56:57], v[26:27], v[56:57] op_sel_hi:[0,1]
	v_pk_mul_f32 v[66:67], v[26:27], v[44:45] op_sel_hi:[0,1]
	v_pk_mul_f32 v[58:59], v[60:61], v[58:59] op_sel_hi:[0,1]
	v_pk_mul_f32 v[60:61], v[60:61], v[46:47] op_sel_hi:[0,1]
	v_pk_mul_f32 v[28:29], v[2:3], v[28:29]
	v_pk_mul_f32 v[26:27], v[0:1], v[62:63]
	v_pk_mul_f32 v[32:33], v[2:3], v[32:33]
	v_pk_mul_f32 v[30:31], v[0:1], v[30:31]
	v_pk_mul_f32 v[36:37], v[6:7], v[36:37]
	v_pk_mul_f32 v[34:35], v[4:5], v[34:35]
	v_pk_mul_f32 v[40:41], v[6:7], v[38:39]
	v_pk_mul_f32 v[38:39], v[4:5], v[48:49]
	v_pk_mul_f32 v[44:45], v[10:11], v[52:53]
	v_pk_mul_f32 v[42:43], v[8:9], v[50:51]
	v_pk_mul_f32 v[48:49], v[10:11], v[64:65]
	v_pk_mul_f32 v[46:47], v[8:9], v[54:55]
	v_pk_mul_f32 v[52:53], v[14:15], v[66:67]
	v_pk_mul_f32 v[50:51], v[12:13], v[56:57]
	v_pk_mul_f32 v[56:57], v[14:15], v[60:61]
	v_pk_mul_f32 v[54:55], v[12:13], v[58:59]
	global_store_dwordx4 v[22:23], v[26:29], off offset:-4096
	global_store_dwordx4 v[22:23], v[30:33], off
	global_store_dwordx4 v[22:23], v[34:37], off offset:-3072
	global_store_dwordx4 v[22:23], v[38:41], off offset:1024
	global_store_dwordx4 v[22:23], v[42:45], off offset:-2048
	global_store_dwordx4 v[22:23], v[46:49], off offset:2048
	global_store_dwordx4 v[22:23], v[50:53], off offset:-1024
	global_store_dwordx4 v[22:23], v[54:57], off offset:3072
	v_lshl_add_u64 v[22:23], v[22:23], 0, s[8:9]
.LBB0_956:
	s_mov_b64 exec, -1
	s_cmp_lg_u32 s66, 0x100
	s_cbranch_scc1 .Lp7s_end
	s_waitcnt vmcnt(16)
	v_mov_b32_e32 v103, 0x358637bd
	v_fmac_f32_e32 v103, 0x3a800000, v102
	v_lshlrev_b32_e32 v110, 16, v100
	v_and_b32_e32 v111, 0xffff0000, v100
	v_rsq_f32_e32 v103, v103
	v_lshlrev_b32_e32 v112, 16, v101
	v_and_b32_e32 v113, 0xffff0000, v101
	v_readlane_b32 s24, v247, 30
	v_readlane_b32 s25, v247, 31
	v_mul_f32_e32 v110, v103, v110
	v_mul_f32_e32 v111, v103, v111
	v_mul_f32_e32 v112, v103, v112
	v_mul_f32_e32 v113, v103, v113
	v_mul_f32_e32 v110, v104, v110
	v_mul_f32_e32 v111, v105, v111
	v_mul_f32_e32 v112, v106, v112
	v_mul_f32_e32 v113, v107, v113
	s_lshl_b32 s23, s21, 12
	s_lshl_b32 s30, s22, 10
	s_add_u32 s23, s23, s30
	s_add_u32 s24, s24, s23
	s_addc_u32 s25, s25, 0
	global_store_dwordx4 v178, v[110:113], s[24:25]
